# DeltaNet scan: s_setprio 3 for the two compute waves that carry the serial chain (staging waves stay at 0)
# speedup vs baseline: 1.0038x; 1.0038x over previous
.LBB0_1379:
	s_or_b64 exec, exec, s[2:3]
	v_readfirstlane_b32 s10, v0
	v_readfirstlane_b32 s11, v1
	v_readfirstlane_b32 s8, v2
	s_nop 3
	s_lshr_b32 s8, s8, 6
	s_and_b32 s5, s6, 1
	s_lshr_b32 s7, s6, 1
	s_mul_i32 s9, s4, 0x2000
	s_add_u32 s12, s10, s9
	s_addc_u32 s13, s11, 0
	s_add_u32 s14, s12, 0x1020000
	s_addc_u32 s15, s13, 0
	s_add_u32 s16, s12, 0x2040000
	s_addc_u32 s17, s13, 0
	s_add_u32 s18, s12, 0x3060000
	s_addc_u32 s19, s13, 0
	s_cmp_lt_u32 s8, 4
	s_cbranch_scc0 .Ldn_loader
	s_cmp_lt_u32 s8, 2
	s_cbranch_scc0 .Ldn_idle
	s_lshl_b32 s3, s5, 1
	s_add_u32 s3, s3, s8
	v_and_b32_e32 v3, 63, v2
	v_and_b32_e32 v4, 15, v2
	v_bfe_u32 v5, v2, 4, 2
	v_mul_u32_u24_e32 v6, 0x90, v4
	v_lshl_add_u32 v6, v5, 3, v6
	v_add_u32_e32 v42, v195, v6
	v_lshlrev_b32_e32 v6, 5, v3
	s_lshl_b32 s9, s3, 11
	v_add3_u32 v43, v195, v6, s9
	v_add_u32_e32 v44, 0x15800, v195
	v_lshlrev_b32_e32 v6, 12, v5
	v_and_b32_e32 v7, 3, v4
	v_lshl_add_u32 v6, v7, 10, v6
	v_lshrrev_b32_e32 v7, 2, v4
	v_lshl_add_u32 v45, v7, 4, v6
	v_and_b32_e32 v6, 1, v2
	v_cmp_eq_u32_e64 s[24:25], 1, v6
	v_and_b32_e32 v6, 2, v2
	v_cmp_eq_u32_e64 s[28:29], 2, v6
	s_nop 3
	s_not_b64 s[26:27], s[24:25]
	s_not_b64 s[30:31], s[28:29]
	v_add_u32_e32 v46, 0x4000, v45
	v_add_u32_e32 v47, 0x8000, v45
	v_add_u32_e32 v48, 0xc000, v45
	s_lshr_b32 s22, s7, 2
	s_mul_i32 s22, s22, 0x1020000
	s_and_b32 s23, s7, 3
	s_lshl_b32 s23, s23, 8
	s_add_u32 s22, s22, s23
	s_lshl_b32 s23, s3, 6
	s_add_u32 s22, s22, s23
	s_add_u32 s22, s22, 0x50a2100
	s_add_u32 s20, s10, s22
	s_addc_u32 s21, s11, 0
	v_mov_b32_e32 v50, 0
	v_mov_b32_e32 v51, 0
	v_mov_b32_e32 v52, 0
	v_mov_b32_e32 v53, 0
	v_mov_b32_e32 v54, 0
	v_mov_b32_e32 v55, 0
	v_mov_b32_e32 v56, 0
	v_mov_b32_e32 v57, 0
	v_mov_b32_e32 v58, 0
	v_mov_b32_e32 v59, 0
	v_mov_b32_e32 v60, 0
	v_mov_b32_e32 v61, 0
	v_mov_b32_e32 v62, 0
	v_mov_b32_e32 v63, 0
	v_mov_b32_e32 v64, 0
	v_mov_b32_e32 v65, 0
	v_mov_b32_e32 v66, 0
	v_mov_b32_e32 v67, 0
	v_mov_b32_e32 v68, 0
	v_mov_b32_e32 v69, 0
	v_mov_b32_e32 v70, 0
	v_mov_b32_e32 v71, 0
	v_mov_b32_e32 v72, 0
	v_mov_b32_e32 v73, 0
	s_mov_b32 s22, 0
	s_waitcnt lgkmcnt(0)
	s_barrier
	s_setprio 3
.Ldn_c_loop:
	ds_read_b32 v154, v44 offset:0
	ds_read_b128 v[138:141], v43 offset:18432
	ds_read_b128 v[142:145], v43 offset:18448
	ds_read_b64 v[74:75], v42 offset:0
	ds_read_b64 v[76:77], v42 offset:32
	ds_read_b64 v[78:79], v42 offset:64
	ds_read_b64 v[80:81], v42 offset:96
	ds_read_b64 v[82:83], v42 offset:2304
	ds_read_b64 v[84:85], v42 offset:2336
	ds_read_b64 v[86:87], v42 offset:2368
	ds_read_b64 v[88:89], v42 offset:2400
	ds_read_b64 v[90:91], v42 offset:4608
	ds_read_b64 v[92:93], v42 offset:4640
	ds_read_b64 v[94:95], v42 offset:4672
	ds_read_b64 v[96:97], v42 offset:4704
	s_waitcnt lgkmcnt(12)
	v_lshlrev_b32_e32 v26, 16, v138
	v_and_b32_e32 v27, 0xffff0000, v138
	ds_read_b64 v[98:99], v42 offset:6912
	v_lshlrev_b32_e32 v28, 16, v139
	v_and_b32_e32 v29, 0xffff0000, v139
	ds_read_b64 v[100:101], v42 offset:6944
	v_lshlrev_b32_e32 v30, 16, v140
	v_and_b32_e32 v31, 0xffff0000, v140
	ds_read_b64 v[102:103], v42 offset:6976
	v_lshlrev_b32_e32 v32, 16, v141
	v_and_b32_e32 v33, 0xffff0000, v141
	ds_read_b64 v[104:105], v42 offset:7008
	v_lshlrev_b32_e32 v34, 16, v142
	v_and_b32_e32 v35, 0xffff0000, v142
	ds_read_b128 v[146:149], v43 offset:26624
	v_lshlrev_b32_e32 v36, 16, v143
	v_and_b32_e32 v37, 0xffff0000, v143
	ds_read_b128 v[150:153], v43 offset:26640
	v_lshlrev_b32_e32 v38, 16, v144
	v_and_b32_e32 v39, 0xffff0000, v144
	v_lshlrev_b32_e32 v40, 16, v145
	v_and_b32_e32 v41, 0xffff0000, v145
	v_fma_f32 v50, v50, v154, v26
	v_fma_f32 v51, v51, v154, v27
	v_fma_f32 v52, v52, v154, v28
	v_fma_f32 v53, v53, v154, v29
	v_fma_f32 v54, v54, v154, v30
	v_fma_f32 v55, v55, v154, v31
	v_fma_f32 v56, v56, v154, v32
	v_fma_f32 v57, v57, v154, v33
	v_fma_f32 v58, v58, v154, v34
	v_fma_f32 v59, v59, v154, v35
	v_fma_f32 v60, v60, v154, v36
	v_fma_f32 v61, v61, v154, v37
	v_fma_f32 v62, v62, v154, v38
	v_fma_f32 v63, v63, v154, v39
	v_fma_f32 v64, v64, v154, v40
	v_fma_f32 v65, v65, v154, v41
	s_waitcnt lgkmcnt(0)
	v_mfma_f32_16x16x32_bf16 v[50:53], v[74:77], v[66:69], v[50:53]
	ds_read_b64 v[106:107], v42 offset:9216
	ds_read_b64 v[108:109], v42 offset:9248
	v_lshlrev_b32_e32 v2, 16, v146
	v_and_b32_e32 v3, 0xffff0000, v146
	v_mfma_f32_16x16x32_bf16 v[54:57], v[82:85], v[66:69], v[54:57]
	ds_read_b64 v[110:111], v42 offset:9280
	ds_read_b64 v[112:113], v42 offset:9312
	v_lshlrev_b32_e32 v4, 16, v147
	v_and_b32_e32 v5, 0xffff0000, v147
	v_mfma_f32_16x16x32_bf16 v[58:61], v[90:93], v[66:69], v[58:61]
	ds_read_b64 v[114:115], v42 offset:11520
	ds_read_b64 v[116:117], v42 offset:11552
	v_lshlrev_b32_e32 v6, 16, v148
	v_and_b32_e32 v7, 0xffff0000, v148
	v_mfma_f32_16x16x32_bf16 v[62:65], v[98:101], v[66:69], v[62:65]
	ds_read_b64 v[118:119], v42 offset:11584
	ds_read_b64 v[120:121], v42 offset:11616
	v_lshlrev_b32_e32 v8, 16, v149
	v_and_b32_e32 v9, 0xffff0000, v149
	v_mfma_f32_16x16x32_bf16 v[50:53], v[78:81], v[70:73], v[50:53]
	ds_read_b64 v[122:123], v42 offset:13824
	ds_read_b64 v[124:125], v42 offset:13856
	v_lshlrev_b32_e32 v10, 16, v150
	v_and_b32_e32 v11, 0xffff0000, v150
	v_mfma_f32_16x16x32_bf16 v[54:57], v[86:89], v[70:73], v[54:57]
	ds_read_b64 v[126:127], v42 offset:13888
	ds_read_b64 v[128:129], v42 offset:13920
	v_lshlrev_b32_e32 v12, 16, v151
	v_and_b32_e32 v13, 0xffff0000, v151
	v_mfma_f32_16x16x32_bf16 v[58:61], v[94:97], v[70:73], v[58:61]
	ds_read_b64 v[130:131], v42 offset:16128
	ds_read_b64 v[132:133], v42 offset:16160
	v_lshlrev_b32_e32 v14, 16, v152
	v_and_b32_e32 v15, 0xffff0000, v152
	v_mfma_f32_16x16x32_bf16 v[62:65], v[102:105], v[70:73], v[62:65]
	ds_read_b64 v[134:135], v42 offset:16192
	ds_read_b64 v[136:137], v42 offset:16224
	v_lshlrev_b32_e32 v16, 16, v153
	v_and_b32_e32 v17, 0xffff0000, v153
	s_waitcnt lgkmcnt(12)
	v_mfma_f32_16x16x32_bf16 v[2:5], v[106:109], v[66:69], v[2:5]
	v_cvt_pk_bf16_f32 v18, v50, v51
	v_mfma_f32_16x16x32_bf16 v[2:5], v[110:113], v[70:73], v[2:5]
	v_cvt_pk_bf16_f32 v19, v52, v53
	s_waitcnt lgkmcnt(8)
	v_mfma_f32_16x16x32_bf16 v[6:9], v[114:117], v[66:69], v[6:9]
	v_cvt_pk_bf16_f32 v20, v54, v55
	v_mfma_f32_16x16x32_bf16 v[6:9], v[118:121], v[70:73], v[6:9]
	v_cvt_pk_bf16_f32 v21, v56, v57
	s_waitcnt lgkmcnt(4)
	v_mfma_f32_16x16x32_bf16 v[10:13], v[122:125], v[66:69], v[10:13]
	v_cvt_pk_bf16_f32 v22, v58, v59
	v_mfma_f32_16x16x32_bf16 v[10:13], v[126:129], v[70:73], v[10:13]
	v_cvt_pk_bf16_f32 v23, v60, v61
	s_waitcnt lgkmcnt(0)
	v_mfma_f32_16x16x32_bf16 v[14:17], v[130:133], v[66:69], v[14:17]
	v_cvt_pk_bf16_f32 v24, v62, v63
	v_mfma_f32_16x16x32_bf16 v[14:17], v[134:137], v[70:73], v[14:17]
	v_cvt_pk_bf16_f32 v25, v64, v65
	s_mov_b64 vcc, s[24:25]
	s_nop 1
	v_cndmask_b32_dpp v27, v2, v3, vcc quad_perm:[1,0,3,2] row_mask:0xf bank_mask:0xf
	v_cndmask_b32_dpp v29, v4, v5, vcc quad_perm:[1,0,3,2] row_mask:0xf bank_mask:0xf
	v_cndmask_b32_dpp v31, v6, v7, vcc quad_perm:[1,0,3,2] row_mask:0xf bank_mask:0xf
	v_cndmask_b32_dpp v33, v8, v9, vcc quad_perm:[1,0,3,2] row_mask:0xf bank_mask:0xf
	v_cndmask_b32_dpp v35, v10, v11, vcc quad_perm:[1,0,3,2] row_mask:0xf bank_mask:0xf
	v_cndmask_b32_dpp v37, v12, v13, vcc quad_perm:[1,0,3,2] row_mask:0xf bank_mask:0xf
	v_cndmask_b32_dpp v39, v14, v15, vcc quad_perm:[1,0,3,2] row_mask:0xf bank_mask:0xf
	v_cndmask_b32_dpp v41, v16, v17, vcc quad_perm:[1,0,3,2] row_mask:0xf bank_mask:0xf
	s_mov_b64 vcc, s[26:27]
	s_nop 1
	v_cndmask_b32_dpp v26, v3, v2, vcc quad_perm:[1,0,3,2] row_mask:0xf bank_mask:0xf
	v_cndmask_b32_dpp v28, v5, v4, vcc quad_perm:[1,0,3,2] row_mask:0xf bank_mask:0xf
	v_cndmask_b32_dpp v30, v7, v6, vcc quad_perm:[1,0,3,2] row_mask:0xf bank_mask:0xf
	v_cndmask_b32_dpp v32, v9, v8, vcc quad_perm:[1,0,3,2] row_mask:0xf bank_mask:0xf
	v_cndmask_b32_dpp v34, v11, v10, vcc quad_perm:[1,0,3,2] row_mask:0xf bank_mask:0xf
	v_cndmask_b32_dpp v36, v13, v12, vcc quad_perm:[1,0,3,2] row_mask:0xf bank_mask:0xf
	v_cndmask_b32_dpp v38, v15, v14, vcc quad_perm:[1,0,3,2] row_mask:0xf bank_mask:0xf
	v_cndmask_b32_dpp v40, v17, v16, vcc quad_perm:[1,0,3,2] row_mask:0xf bank_mask:0xf
	s_mov_b64 vcc, s[28:29]
	s_nop 1
	v_cndmask_b32_dpp v4, v26, v28, vcc quad_perm:[2,3,0,1] row_mask:0xf bank_mask:0xf
	v_cndmask_b32_dpp v5, v27, v29, vcc quad_perm:[2,3,0,1] row_mask:0xf bank_mask:0xf
	v_cndmask_b32_dpp v8, v30, v32, vcc quad_perm:[2,3,0,1] row_mask:0xf bank_mask:0xf
	v_cndmask_b32_dpp v9, v31, v33, vcc quad_perm:[2,3,0,1] row_mask:0xf bank_mask:0xf
	v_cndmask_b32_dpp v12, v34, v36, vcc quad_perm:[2,3,0,1] row_mask:0xf bank_mask:0xf
	v_cndmask_b32_dpp v13, v35, v37, vcc quad_perm:[2,3,0,1] row_mask:0xf bank_mask:0xf
	v_cndmask_b32_dpp v16, v38, v40, vcc quad_perm:[2,3,0,1] row_mask:0xf bank_mask:0xf
	v_cndmask_b32_dpp v17, v39, v41, vcc quad_perm:[2,3,0,1] row_mask:0xf bank_mask:0xf
	s_mov_b64 vcc, s[30:31]
	s_nop 1
	v_cndmask_b32_dpp v2, v28, v26, vcc quad_perm:[2,3,0,1] row_mask:0xf bank_mask:0xf
	v_cndmask_b32_dpp v3, v29, v27, vcc quad_perm:[2,3,0,1] row_mask:0xf bank_mask:0xf
	v_cndmask_b32_dpp v6, v32, v30, vcc quad_perm:[2,3,0,1] row_mask:0xf bank_mask:0xf
	v_cndmask_b32_dpp v7, v33, v31, vcc quad_perm:[2,3,0,1] row_mask:0xf bank_mask:0xf
	v_cndmask_b32_dpp v10, v36, v34, vcc quad_perm:[2,3,0,1] row_mask:0xf bank_mask:0xf
	v_cndmask_b32_dpp v11, v37, v35, vcc quad_perm:[2,3,0,1] row_mask:0xf bank_mask:0xf
	v_cndmask_b32_dpp v14, v40, v38, vcc quad_perm:[2,3,0,1] row_mask:0xf bank_mask:0xf
	v_cndmask_b32_dpp v15, v41, v39, vcc quad_perm:[2,3,0,1] row_mask:0xf bank_mask:0xf
	global_store_dwordx4 v45, v[2:5], s[20:21]
	global_store_dwordx4 v46, v[6:9], s[20:21]
	global_store_dwordx4 v47, v[10:13], s[20:21]
	global_store_dwordx4 v48, v[14:17], s[20:21]
	s_add_u32 s20, s20, 0x10000
	s_addc_u32 s21, s21, 0
	s_waitcnt lgkmcnt(0)
	s_barrier
	ds_read_b32 v154, v44 offset:4
	ds_read_b128 v[138:141], v43 offset:53248
	ds_read_b128 v[142:145], v43 offset:53264
	ds_read_b64 v[74:75], v42 offset:34816
	ds_read_b64 v[76:77], v42 offset:34848
	ds_read_b64 v[78:79], v42 offset:34880
	ds_read_b64 v[80:81], v42 offset:34912
	ds_read_b64 v[82:83], v42 offset:37120
	ds_read_b64 v[84:85], v42 offset:37152
	ds_read_b64 v[86:87], v42 offset:37184
	ds_read_b64 v[88:89], v42 offset:37216
	ds_read_b64 v[90:91], v42 offset:39424
	ds_read_b64 v[92:93], v42 offset:39456
	ds_read_b64 v[94:95], v42 offset:39488
	ds_read_b64 v[96:97], v42 offset:39520
	s_waitcnt lgkmcnt(12)
	v_lshlrev_b32_e32 v26, 16, v138
	v_and_b32_e32 v27, 0xffff0000, v138
	ds_read_b64 v[98:99], v42 offset:41728
	v_lshlrev_b32_e32 v28, 16, v139
	v_and_b32_e32 v29, 0xffff0000, v139
	ds_read_b64 v[100:101], v42 offset:41760
	v_lshlrev_b32_e32 v30, 16, v140
	v_and_b32_e32 v31, 0xffff0000, v140
	ds_read_b64 v[102:103], v42 offset:41792
	v_lshlrev_b32_e32 v32, 16, v141
	v_and_b32_e32 v33, 0xffff0000, v141
	ds_read_b64 v[104:105], v42 offset:41824
	v_lshlrev_b32_e32 v34, 16, v142
	v_and_b32_e32 v35, 0xffff0000, v142
	ds_read_b128 v[146:149], v43 offset:61440
	v_lshlrev_b32_e32 v36, 16, v143
	v_and_b32_e32 v37, 0xffff0000, v143
	ds_read_b128 v[150:153], v43 offset:61456
	v_lshlrev_b32_e32 v38, 16, v144
	v_and_b32_e32 v39, 0xffff0000, v144
	v_lshlrev_b32_e32 v40, 16, v145
	v_and_b32_e32 v41, 0xffff0000, v145
	v_fma_f32 v50, v50, v154, v26
	v_fma_f32 v51, v51, v154, v27
	v_fma_f32 v52, v52, v154, v28
	v_fma_f32 v53, v53, v154, v29
	v_fma_f32 v54, v54, v154, v30
	v_fma_f32 v55, v55, v154, v31
	v_fma_f32 v56, v56, v154, v32
	v_fma_f32 v57, v57, v154, v33
	v_fma_f32 v58, v58, v154, v34
	v_fma_f32 v59, v59, v154, v35
	v_fma_f32 v60, v60, v154, v36
	v_fma_f32 v61, v61, v154, v37
	v_fma_f32 v62, v62, v154, v38
	v_fma_f32 v63, v63, v154, v39
	v_fma_f32 v64, v64, v154, v40
	v_fma_f32 v65, v65, v154, v41
	s_waitcnt lgkmcnt(0)
	v_mfma_f32_16x16x32_bf16 v[50:53], v[74:77], v[18:21], v[50:53]
	ds_read_b64 v[106:107], v42 offset:44032
	ds_read_b64 v[108:109], v42 offset:44064
	v_lshlrev_b32_e32 v2, 16, v146
	v_and_b32_e32 v3, 0xffff0000, v146
	v_mfma_f32_16x16x32_bf16 v[54:57], v[82:85], v[18:21], v[54:57]
	ds_read_b64 v[110:111], v42 offset:44096
	ds_read_b64 v[112:113], v42 offset:44128
	v_lshlrev_b32_e32 v4, 16, v147
	v_and_b32_e32 v5, 0xffff0000, v147
	v_mfma_f32_16x16x32_bf16 v[58:61], v[90:93], v[18:21], v[58:61]
	ds_read_b64 v[114:115], v42 offset:46336
	ds_read_b64 v[116:117], v42 offset:46368
	v_lshlrev_b32_e32 v6, 16, v148
	v_and_b32_e32 v7, 0xffff0000, v148
	v_mfma_f32_16x16x32_bf16 v[62:65], v[98:101], v[18:21], v[62:65]
	ds_read_b64 v[118:119], v42 offset:46400
	ds_read_b64 v[120:121], v42 offset:46432
	v_lshlrev_b32_e32 v8, 16, v149
	v_and_b32_e32 v9, 0xffff0000, v149
	v_mfma_f32_16x16x32_bf16 v[50:53], v[78:81], v[22:25], v[50:53]
	ds_read_b64 v[122:123], v42 offset:48640
	ds_read_b64 v[124:125], v42 offset:48672
	v_lshlrev_b32_e32 v10, 16, v150
	v_and_b32_e32 v11, 0xffff0000, v150
	v_mfma_f32_16x16x32_bf16 v[54:57], v[86:89], v[22:25], v[54:57]
	ds_read_b64 v[126:127], v42 offset:48704
	ds_read_b64 v[128:129], v42 offset:48736
	v_lshlrev_b32_e32 v12, 16, v151
	v_and_b32_e32 v13, 0xffff0000, v151
	v_mfma_f32_16x16x32_bf16 v[58:61], v[94:97], v[22:25], v[58:61]
	ds_read_b64 v[130:131], v42 offset:50944
	ds_read_b64 v[132:133], v42 offset:50976
	v_lshlrev_b32_e32 v14, 16, v152
	v_and_b32_e32 v15, 0xffff0000, v152
	v_mfma_f32_16x16x32_bf16 v[62:65], v[102:105], v[22:25], v[62:65]
	ds_read_b64 v[134:135], v42 offset:51008
	ds_read_b64 v[136:137], v42 offset:51040
	v_lshlrev_b32_e32 v16, 16, v153
	v_and_b32_e32 v17, 0xffff0000, v153
	s_waitcnt lgkmcnt(12)
	v_mfma_f32_16x16x32_bf16 v[2:5], v[106:109], v[18:21], v[2:5]
	v_cvt_pk_bf16_f32 v66, v50, v51
	v_mfma_f32_16x16x32_bf16 v[2:5], v[110:113], v[22:25], v[2:5]
	v_cvt_pk_bf16_f32 v67, v52, v53
	s_waitcnt lgkmcnt(8)
	v_mfma_f32_16x16x32_bf16 v[6:9], v[114:117], v[18:21], v[6:9]
	v_cvt_pk_bf16_f32 v68, v54, v55
	v_mfma_f32_16x16x32_bf16 v[6:9], v[118:121], v[22:25], v[6:9]
	v_cvt_pk_bf16_f32 v69, v56, v57
	s_waitcnt lgkmcnt(4)
	v_mfma_f32_16x16x32_bf16 v[10:13], v[122:125], v[18:21], v[10:13]
	v_cvt_pk_bf16_f32 v70, v58, v59
	v_mfma_f32_16x16x32_bf16 v[10:13], v[126:129], v[22:25], v[10:13]
	v_cvt_pk_bf16_f32 v71, v60, v61
	s_waitcnt lgkmcnt(0)
	v_mfma_f32_16x16x32_bf16 v[14:17], v[130:133], v[18:21], v[14:17]
	v_cvt_pk_bf16_f32 v72, v62, v63
	v_mfma_f32_16x16x32_bf16 v[14:17], v[134:137], v[22:25], v[14:17]
	v_cvt_pk_bf16_f32 v73, v64, v65
	s_mov_b64 vcc, s[24:25]
	s_nop 1
	v_cndmask_b32_dpp v27, v2, v3, vcc quad_perm:[1,0,3,2] row_mask:0xf bank_mask:0xf
	v_cndmask_b32_dpp v29, v4, v5, vcc quad_perm:[1,0,3,2] row_mask:0xf bank_mask:0xf
	v_cndmask_b32_dpp v31, v6, v7, vcc quad_perm:[1,0,3,2] row_mask:0xf bank_mask:0xf
	v_cndmask_b32_dpp v33, v8, v9, vcc quad_perm:[1,0,3,2] row_mask:0xf bank_mask:0xf
	v_cndmask_b32_dpp v35, v10, v11, vcc quad_perm:[1,0,3,2] row_mask:0xf bank_mask:0xf
	v_cndmask_b32_dpp v37, v12, v13, vcc quad_perm:[1,0,3,2] row_mask:0xf bank_mask:0xf
	v_cndmask_b32_dpp v39, v14, v15, vcc quad_perm:[1,0,3,2] row_mask:0xf bank_mask:0xf
	v_cndmask_b32_dpp v41, v16, v17, vcc quad_perm:[1,0,3,2] row_mask:0xf bank_mask:0xf
	s_mov_b64 vcc, s[26:27]
	s_nop 1
	v_cndmask_b32_dpp v26, v3, v2, vcc quad_perm:[1,0,3,2] row_mask:0xf bank_mask:0xf
	v_cndmask_b32_dpp v28, v5, v4, vcc quad_perm:[1,0,3,2] row_mask:0xf bank_mask:0xf
	v_cndmask_b32_dpp v30, v7, v6, vcc quad_perm:[1,0,3,2] row_mask:0xf bank_mask:0xf
	v_cndmask_b32_dpp v32, v9, v8, vcc quad_perm:[1,0,3,2] row_mask:0xf bank_mask:0xf
	v_cndmask_b32_dpp v34, v11, v10, vcc quad_perm:[1,0,3,2] row_mask:0xf bank_mask:0xf
	v_cndmask_b32_dpp v36, v13, v12, vcc quad_perm:[1,0,3,2] row_mask:0xf bank_mask:0xf
	v_cndmask_b32_dpp v38, v15, v14, vcc quad_perm:[1,0,3,2] row_mask:0xf bank_mask:0xf
	v_cndmask_b32_dpp v40, v17, v16, vcc quad_perm:[1,0,3,2] row_mask:0xf bank_mask:0xf
	s_mov_b64 vcc, s[28:29]
	s_nop 1
	v_cndmask_b32_dpp v4, v26, v28, vcc quad_perm:[2,3,0,1] row_mask:0xf bank_mask:0xf
	v_cndmask_b32_dpp v5, v27, v29, vcc quad_perm:[2,3,0,1] row_mask:0xf bank_mask:0xf
	v_cndmask_b32_dpp v8, v30, v32, vcc quad_perm:[2,3,0,1] row_mask:0xf bank_mask:0xf
	v_cndmask_b32_dpp v9, v31, v33, vcc quad_perm:[2,3,0,1] row_mask:0xf bank_mask:0xf
	v_cndmask_b32_dpp v12, v34, v36, vcc quad_perm:[2,3,0,1] row_mask:0xf bank_mask:0xf
	v_cndmask_b32_dpp v13, v35, v37, vcc quad_perm:[2,3,0,1] row_mask:0xf bank_mask:0xf
	v_cndmask_b32_dpp v16, v38, v40, vcc quad_perm:[2,3,0,1] row_mask:0xf bank_mask:0xf
	v_cndmask_b32_dpp v17, v39, v41, vcc quad_perm:[2,3,0,1] row_mask:0xf bank_mask:0xf
	s_mov_b64 vcc, s[30:31]
	s_nop 1
	v_cndmask_b32_dpp v2, v28, v26, vcc quad_perm:[2,3,0,1] row_mask:0xf bank_mask:0xf
	v_cndmask_b32_dpp v3, v29, v27, vcc quad_perm:[2,3,0,1] row_mask:0xf bank_mask:0xf
	v_cndmask_b32_dpp v6, v32, v30, vcc quad_perm:[2,3,0,1] row_mask:0xf bank_mask:0xf
	v_cndmask_b32_dpp v7, v33, v31, vcc quad_perm:[2,3,0,1] row_mask:0xf bank_mask:0xf
	v_cndmask_b32_dpp v10, v36, v34, vcc quad_perm:[2,3,0,1] row_mask:0xf bank_mask:0xf
	v_cndmask_b32_dpp v11, v37, v35, vcc quad_perm:[2,3,0,1] row_mask:0xf bank_mask:0xf
	v_cndmask_b32_dpp v14, v40, v38, vcc quad_perm:[2,3,0,1] row_mask:0xf bank_mask:0xf
	v_cndmask_b32_dpp v15, v41, v39, vcc quad_perm:[2,3,0,1] row_mask:0xf bank_mask:0xf
	global_store_dwordx4 v45, v[2:5], s[20:21]
	global_store_dwordx4 v46, v[6:9], s[20:21]
	global_store_dwordx4 v47, v[10:13], s[20:21]
	global_store_dwordx4 v48, v[14:17], s[20:21]
	s_add_u32 s20, s20, 0x10000
	s_addc_u32 s21, s21, 0
	v_add_u32_e32 v44, 8, v44
	s_add_u32 s22, s22, 1
	s_waitcnt lgkmcnt(0)
	s_barrier
	s_cmp_lt_u32 s22, 0x81
	s_cbranch_scc1 .Ldn_c_loop
	s_setprio 0
	s_branch .LBB0_1387
